# v13 + P9 SwiGLU epilogue: four-element groups with packed f32 mul/add and back-to-back exp/rcp (bit-identical math, 16 instead of 32 VALU per four elements, no s_nop)
# speedup vs baseline: 1.0006x; 1.0006x over previous
; __device__ __forceinline__ unsigned cvt_pk_bf16(float lo, float hi) { unsigned r; asm volatile("v_cvt_pk_bf16_f32 %0, %1, %2" : "=v"(r) : "v"(lo), "v"(hi)); return r; }
; __device__ __forceinline__ float sigmoidf_(float x) { return __builtin_amdgcn_rcpf(1.0f + __expf(-x)); }
;     __device__ __forceinline__ void operator()(const f32x4 (&acc)[2][2][4][2], const Unit& u, int wr, int wc, int fr, int fq) const {
;         const int row0 = u.pm * 256 + wr * 64 + fr; const int col0 = u.pn * 128 + wc * 32 + 8 * fq;
; #pragma unroll
;         for (int ai = 0; ai < 2; ++ai)
; #pragma unroll
;             for (int m = 0; m < 4; ++m) {
;                 float o[8];
; #pragma unroll
;                 for (int n = 0; n < 2; ++n)
; #pragma unroll
;                     for (int i = 0; i < 4; ++i) { const float a = acc[ai][0][m][n][i], b = acc[ai][1][m][n][i]; o[n * 4 + i] = a * sigmoidf_(a) * b; }
;                 u32x4 w; w.x = cvt_pk_bf16(o[0], o[1]); w.y = cvt_pk_bf16(o[2], o[3]); w.z = cvt_pk_bf16(o[4], o[5]); w.w = cvt_pk_bf16(o[6], o[7]);
;                 *(u32x4*)(H + (size_t)(row0 + ai * HALF + m * 16) * FF + col0) = w;
;             }
.LBB0_838:
	s_mov_b32 s98, 0xbfb8aa3b
	s_mov_b32 s99, 0xbfb8aa3b
	v_pk_mul_f32 v[244:245], v[124:125], s[98:99] op_sel_hi:[1,0]
	v_pk_mul_f32 v[246:247], v[126:127], s[98:99] op_sel_hi:[1,0]
	v_exp_f32_e32 v244, v244
	v_exp_f32_e32 v245, v245
	v_exp_f32_e32 v246, v246
	v_exp_f32_e32 v247, v247
	v_pk_add_f32 v[244:245], v[244:245], 1.0 op_sel_hi:[1,0]
	v_pk_add_f32 v[246:247], v[246:247], 1.0 op_sel_hi:[1,0]
	v_rcp_f32_e32 v244, v244
	v_rcp_f32_e32 v245, v245
	v_rcp_f32_e32 v246, v246
	v_rcp_f32_e32 v247, v247
	v_pk_mul_f32 v[124:125], v[124:125], v[244:245]
	v_pk_mul_f32 v[126:127], v[126:127], v[246:247]
	v_pk_mul_f32 v[120:121], v[124:125], v[120:121]
	v_pk_mul_f32 v[122:123], v[126:127], v[122:123]
	v_lshl_add_u32 v152, s19, 7, v146
	v_lshl_add_u32 v150, s18, 8, v144
	v_ashrrev_i32_e32 v153, 31, v152
	s_andn2_b64 vcc, exec, s[0:1]
	v_pk_mul_f32 v[244:245], v[116:117], s[98:99] op_sel_hi:[1,0]
	v_pk_mul_f32 v[246:247], v[118:119], s[98:99] op_sel_hi:[1,0]
	v_exp_f32_e32 v244, v244
	v_exp_f32_e32 v245, v245
	v_exp_f32_e32 v246, v246
	v_exp_f32_e32 v247, v247
	v_pk_add_f32 v[244:245], v[244:245], 1.0 op_sel_hi:[1,0]
	v_pk_add_f32 v[246:247], v[246:247], 1.0 op_sel_hi:[1,0]
	v_rcp_f32_e32 v244, v244
	v_rcp_f32_e32 v245, v245
	v_rcp_f32_e32 v246, v246
	v_rcp_f32_e32 v247, v247
	v_pk_mul_f32 v[116:117], v[116:117], v[244:245]
	v_pk_mul_f32 v[118:119], v[118:119], v[246:247]
	v_pk_mul_f32 v[112:113], v[116:117], v[112:113]
	v_pk_mul_f32 v[114:115], v[118:119], v[114:115]
	v_cvt_pk_bf16_f32 v116, v120, v121
	v_cvt_pk_bf16_f32 v117, v122, v123
	v_cvt_pk_bf16_f32 v118, v112, v113
	v_mov_b64_e32 v[112:113], s[60:61]
	v_cvt_pk_bf16_f32 v119, v114, v115
	v_mad_i64_i32 v[120:121], s[18:19], v150, s47, v[112:113]
	v_lshlrev_b64 v[114:115], 1, v[152:153]
	v_lshl_add_u64 v[120:121], v[120:121], 0, v[114:115]
	global_store_dwordx4 v[120:121], v[116:119], off
	s_nop 1
	v_pk_mul_f32 v[244:245], v[108:109], s[98:99] op_sel_hi:[1,0]
	v_pk_mul_f32 v[246:247], v[110:111], s[98:99] op_sel_hi:[1,0]
	v_exp_f32_e32 v244, v244
	v_exp_f32_e32 v245, v245
	v_exp_f32_e32 v246, v246
	v_exp_f32_e32 v247, v247
	v_pk_add_f32 v[244:245], v[244:245], 1.0 op_sel_hi:[1,0]
	v_pk_add_f32 v[246:247], v[246:247], 1.0 op_sel_hi:[1,0]
	v_rcp_f32_e32 v244, v244
	v_rcp_f32_e32 v245, v245
	v_rcp_f32_e32 v246, v246
	v_rcp_f32_e32 v247, v247
	v_pk_mul_f32 v[108:109], v[108:109], v[244:245]
	v_pk_mul_f32 v[110:111], v[110:111], v[246:247]
	v_pk_mul_f32 v[104:105], v[108:109], v[104:105]
	v_pk_mul_f32 v[106:107], v[110:111], v[106:107]
	v_pk_mul_f32 v[244:245], v[100:101], s[98:99] op_sel_hi:[1,0]
	v_pk_mul_f32 v[246:247], v[102:103], s[98:99] op_sel_hi:[1,0]
	v_exp_f32_e32 v244, v244
	v_exp_f32_e32 v245, v245
	v_exp_f32_e32 v246, v246
	v_exp_f32_e32 v247, v247
	v_pk_add_f32 v[244:245], v[244:245], 1.0 op_sel_hi:[1,0]
	v_pk_add_f32 v[246:247], v[246:247], 1.0 op_sel_hi:[1,0]
	v_rcp_f32_e32 v244, v244
	v_rcp_f32_e32 v245, v245
	v_rcp_f32_e32 v246, v246
	v_rcp_f32_e32 v247, v247
	v_pk_mul_f32 v[100:101], v[100:101], v[244:245]
	v_pk_mul_f32 v[102:103], v[102:103], v[246:247]
	v_pk_mul_f32 v[100:101], v[100:101], v[96:97]
	v_pk_mul_f32 v[98:99], v[102:103], v[98:99]
	v_mov_b32_e32 v102, v98
	v_cvt_pk_bf16_f32 v96, v104, v105
	v_cvt_pk_bf16_f32 v97, v106, v107
	v_cvt_pk_bf16_f32 v98, v100, v101
	v_or_b32_e32 v100, 16, v150
	v_mad_i64_i32 v[100:101], s[18:19], v100, s47, v[112:113]
	v_lshl_add_u64 v[100:101], v[100:101], 0, v[114:115]
	v_cvt_pk_bf16_f32 v99, v102, v99
	global_store_dwordx4 v[100:101], v[96:99], off
	s_nop 1
	v_pk_mul_f32 v[244:245], v[92:93], s[98:99] op_sel_hi:[1,0]
	v_pk_mul_f32 v[246:247], v[94:95], s[98:99] op_sel_hi:[1,0]
	v_exp_f32_e32 v244, v244
	v_exp_f32_e32 v245, v245
	v_exp_f32_e32 v246, v246
	v_exp_f32_e32 v247, v247
	v_pk_add_f32 v[244:245], v[244:245], 1.0 op_sel_hi:[1,0]
	v_pk_add_f32 v[246:247], v[246:247], 1.0 op_sel_hi:[1,0]
	v_rcp_f32_e32 v244, v244
	v_rcp_f32_e32 v245, v245
	v_rcp_f32_e32 v246, v246
	v_rcp_f32_e32 v247, v247
	v_pk_mul_f32 v[92:93], v[92:93], v[244:245]
	v_pk_mul_f32 v[94:95], v[94:95], v[246:247]
	v_pk_mul_f32 v[88:89], v[92:93], v[88:89]
	v_pk_mul_f32 v[90:91], v[94:95], v[90:91]
	v_pk_mul_f32 v[244:245], v[84:85], s[98:99] op_sel_hi:[1,0]
	v_pk_mul_f32 v[246:247], v[86:87], s[98:99] op_sel_hi:[1,0]
	v_exp_f32_e32 v244, v244
	v_exp_f32_e32 v245, v245
	v_exp_f32_e32 v246, v246
	v_exp_f32_e32 v247, v247
	v_pk_add_f32 v[244:245], v[244:245], 1.0 op_sel_hi:[1,0]
	v_pk_add_f32 v[246:247], v[246:247], 1.0 op_sel_hi:[1,0]
	v_rcp_f32_e32 v244, v244
	v_rcp_f32_e32 v245, v245
	v_rcp_f32_e32 v246, v246
	v_rcp_f32_e32 v247, v247
	v_pk_mul_f32 v[84:85], v[84:85], v[244:245]
	v_pk_mul_f32 v[86:87], v[86:87], v[246:247]
	v_pk_mul_f32 v[84:85], v[84:85], v[80:81]
	v_pk_mul_f32 v[82:83], v[86:87], v[82:83]
	v_mov_b32_e32 v86, v82
	v_cvt_pk_bf16_f32 v80, v88, v89
	v_cvt_pk_bf16_f32 v81, v90, v91
	v_cvt_pk_bf16_f32 v82, v84, v85
	v_or_b32_e32 v84, 32, v150
	v_mad_i64_i32 v[84:85], s[18:19], v84, s47, v[112:113]
	v_lshl_add_u64 v[84:85], v[84:85], 0, v[114:115]
	v_cvt_pk_bf16_f32 v83, v86, v83
	global_store_dwordx4 v[84:85], v[80:83], off
	s_nop 1
	v_pk_mul_f32 v[244:245], v[76:77], s[98:99] op_sel_hi:[1,0]
	v_pk_mul_f32 v[246:247], v[78:79], s[98:99] op_sel_hi:[1,0]
	v_exp_f32_e32 v244, v244
	v_exp_f32_e32 v245, v245
	v_exp_f32_e32 v246, v246
	v_exp_f32_e32 v247, v247
	v_pk_add_f32 v[244:245], v[244:245], 1.0 op_sel_hi:[1,0]
	v_pk_add_f32 v[246:247], v[246:247], 1.0 op_sel_hi:[1,0]
	v_rcp_f32_e32 v244, v244
	v_rcp_f32_e32 v245, v245
	v_rcp_f32_e32 v246, v246
	v_rcp_f32_e32 v247, v247
	v_pk_mul_f32 v[76:77], v[76:77], v[244:245]
	v_pk_mul_f32 v[78:79], v[78:79], v[246:247]
; __device__ __forceinline__ unsigned cvt_pk_bf16(float lo, float hi) { unsigned r; asm volatile("v_cvt_pk_bf16_f32 %0, %1, %2" : "=v"(r) : "v"(lo), "v"(hi)); return r; }
; __device__ __forceinline__ float sigmoidf_(float x) { return __builtin_amdgcn_rcpf(1.0f + __expf(-x)); }
;     __device__ __forceinline__ void operator()(const f32x4 (&acc)[2][2][4][2], const Unit& u, int wr, int wc, int fr, int fq) const {
;     ...
;                     for (int i = 0; i < 4; ++i) { const float a = acc[ai][0][m][n][i], b = acc[ai][1][m][n][i]; o[n * 4 + i] = a * sigmoidf_(a) * b; }
;                 u32x4 w; w.x = cvt_pk_bf16(o[0], o[1]); w.y = cvt_pk_bf16(o[2], o[3]); w.z = cvt_pk_bf16(o[4], o[5]); w.w = cvt_pk_bf16(o[6], o[7]);
;                 *(u32x4*)(H + (size_t)(row0 + ai * HALF + m * 16) * FF + col0) = w;
	v_pk_mul_f32 v[72:73], v[76:77], v[72:73]
	v_pk_mul_f32 v[74:75], v[78:79], v[74:75]
	v_pk_mul_f32 v[244:245], v[68:69], s[98:99] op_sel_hi:[1,0]
	v_pk_mul_f32 v[246:247], v[70:71], s[98:99] op_sel_hi:[1,0]
	v_exp_f32_e32 v244, v244
	v_exp_f32_e32 v245, v245
	v_exp_f32_e32 v246, v246
	v_exp_f32_e32 v247, v247
	v_pk_add_f32 v[244:245], v[244:245], 1.0 op_sel_hi:[1,0]
	v_pk_add_f32 v[246:247], v[246:247], 1.0 op_sel_hi:[1,0]
	v_rcp_f32_e32 v244, v244
	v_rcp_f32_e32 v245, v245
	v_rcp_f32_e32 v246, v246
	v_rcp_f32_e32 v247, v247
	v_pk_mul_f32 v[68:69], v[68:69], v[244:245]
	v_pk_mul_f32 v[70:71], v[70:71], v[246:247]
	v_pk_mul_f32 v[68:69], v[68:69], v[64:65]
	v_pk_mul_f32 v[66:67], v[70:71], v[66:67]
	v_mov_b32_e32 v70, v66
	v_cvt_pk_bf16_f32 v64, v72, v73
	v_cvt_pk_bf16_f32 v65, v74, v75
	v_cvt_pk_bf16_f32 v66, v68, v69
	v_or_b32_e32 v68, 48, v150
	v_mad_i64_i32 v[68:69], s[18:19], v68, s47, v[112:113]
	v_lshl_add_u64 v[68:69], v[68:69], 0, v[114:115]
	v_cvt_pk_bf16_f32 v67, v70, v67
	global_store_dwordx4 v[68:69], v[64:67], off
	s_nop 1
	v_pk_mul_f32 v[244:245], v[60:61], s[98:99] op_sel_hi:[1,0]
	v_pk_mul_f32 v[246:247], v[62:63], s[98:99] op_sel_hi:[1,0]
	v_exp_f32_e32 v244, v244
	v_exp_f32_e32 v245, v245
	v_exp_f32_e32 v246, v246
	v_exp_f32_e32 v247, v247
	v_pk_add_f32 v[244:245], v[244:245], 1.0 op_sel_hi:[1,0]
	v_pk_add_f32 v[246:247], v[246:247], 1.0 op_sel_hi:[1,0]
	v_rcp_f32_e32 v244, v244
	v_rcp_f32_e32 v245, v245
	v_rcp_f32_e32 v246, v246
	v_rcp_f32_e32 v247, v247
	v_pk_mul_f32 v[60:61], v[60:61], v[244:245]
	v_pk_mul_f32 v[62:63], v[62:63], v[246:247]
	v_pk_mul_f32 v[56:57], v[60:61], v[56:57]
	v_pk_mul_f32 v[58:59], v[62:63], v[58:59]
	v_add_u32_e32 v64, 0x80, v150
	v_pk_mul_f32 v[244:245], v[52:53], s[98:99] op_sel_hi:[1,0]
	v_pk_mul_f32 v[246:247], v[54:55], s[98:99] op_sel_hi:[1,0]
	v_exp_f32_e32 v244, v244
	v_exp_f32_e32 v245, v245
	v_exp_f32_e32 v246, v246
	v_exp_f32_e32 v247, v247
	v_pk_add_f32 v[244:245], v[244:245], 1.0 op_sel_hi:[1,0]
	v_pk_add_f32 v[246:247], v[246:247], 1.0 op_sel_hi:[1,0]
	v_rcp_f32_e32 v244, v244
	v_rcp_f32_e32 v245, v245
	v_rcp_f32_e32 v246, v246
	v_rcp_f32_e32 v247, v247
	v_pk_mul_f32 v[52:53], v[52:53], v[244:245]
	v_pk_mul_f32 v[54:55], v[54:55], v[246:247]
	v_pk_mul_f32 v[52:53], v[52:53], v[48:49]
	v_pk_mul_f32 v[50:51], v[54:55], v[50:51]
	v_mov_b32_e32 v54, v50
	v_cvt_pk_bf16_f32 v48, v56, v57
	v_cvt_pk_bf16_f32 v49, v58, v59
	v_cvt_pk_bf16_f32 v50, v52, v53
	v_mad_i64_i32 v[52:53], s[18:19], v64, s47, v[112:113]
	v_lshl_add_u64 v[52:53], v[52:53], 0, v[114:115]
	v_cvt_pk_bf16_f32 v51, v54, v51
	global_store_dwordx4 v[52:53], v[48:51], off
	s_nop 1
	v_pk_mul_f32 v[244:245], v[44:45], s[98:99] op_sel_hi:[1,0]
	v_pk_mul_f32 v[246:247], v[46:47], s[98:99] op_sel_hi:[1,0]
	v_exp_f32_e32 v244, v244
	v_exp_f32_e32 v245, v245
	v_exp_f32_e32 v246, v246
	v_exp_f32_e32 v247, v247
	v_pk_add_f32 v[244:245], v[244:245], 1.0 op_sel_hi:[1,0]
	v_pk_add_f32 v[246:247], v[246:247], 1.0 op_sel_hi:[1,0]
	v_rcp_f32_e32 v244, v244
	v_rcp_f32_e32 v245, v245
	v_rcp_f32_e32 v246, v246
	v_rcp_f32_e32 v247, v247
	v_pk_mul_f32 v[44:45], v[44:45], v[244:245]
	v_pk_mul_f32 v[46:47], v[46:47], v[246:247]
	v_pk_mul_f32 v[40:41], v[44:45], v[40:41]
	v_pk_mul_f32 v[42:43], v[46:47], v[42:43]
	v_pk_mul_f32 v[244:245], v[36:37], s[98:99] op_sel_hi:[1,0]
	v_pk_mul_f32 v[246:247], v[38:39], s[98:99] op_sel_hi:[1,0]
	v_exp_f32_e32 v244, v244
	v_exp_f32_e32 v245, v245
	v_exp_f32_e32 v246, v246
	v_exp_f32_e32 v247, v247
	v_pk_add_f32 v[244:245], v[244:245], 1.0 op_sel_hi:[1,0]
	v_pk_add_f32 v[246:247], v[246:247], 1.0 op_sel_hi:[1,0]
	v_rcp_f32_e32 v244, v244
	v_rcp_f32_e32 v245, v245
	v_rcp_f32_e32 v246, v246
	v_rcp_f32_e32 v247, v247
	v_pk_mul_f32 v[36:37], v[36:37], v[244:245]
; __device__ __forceinline__ unsigned cvt_pk_bf16(float lo, float hi) { unsigned r; asm volatile("v_cvt_pk_bf16_f32 %0, %1, %2" : "=v"(r) : "v"(lo), "v"(hi)); return r; }
; __device__ __forceinline__ float sigmoidf_(float x) { return __builtin_amdgcn_rcpf(1.0f + __expf(-x)); }
;     __device__ __forceinline__ void operator()(const f32x4 (&acc)[2][2][4][2], const Unit& u, int wr, int wc, int fr, int fq) const {
;     ...
;                     for (int i = 0; i < 4; ++i) { const float a = acc[ai][0][m][n][i], b = acc[ai][1][m][n][i]; o[n * 4 + i] = a * sigmoidf_(a) * b; }
;                 u32x4 w; w.x = cvt_pk_bf16(o[0], o[1]); w.y = cvt_pk_bf16(o[2], o[3]); w.z = cvt_pk_bf16(o[4], o[5]); w.w = cvt_pk_bf16(o[6], o[7]);
;                 *(u32x4*)(H + (size_t)(row0 + ai * HALF + m * 16) * FF + col0) = w;
;             }
	v_pk_mul_f32 v[38:39], v[38:39], v[246:247]
	v_pk_mul_f32 v[36:37], v[36:37], v[32:33]
	v_pk_mul_f32 v[34:35], v[38:39], v[34:35]
	v_mov_b32_e32 v38, v34
	v_cvt_pk_bf16_f32 v32, v40, v41
	v_cvt_pk_bf16_f32 v33, v42, v43
	v_cvt_pk_bf16_f32 v34, v36, v37
	v_add_u32_e32 v36, 0x90, v150
	v_mad_i64_i32 v[36:37], s[18:19], v36, s47, v[112:113]
	v_lshl_add_u64 v[36:37], v[36:37], 0, v[114:115]
	v_cvt_pk_bf16_f32 v35, v38, v35
	global_store_dwordx4 v[36:37], v[32:35], off
	s_nop 1
	v_pk_mul_f32 v[244:245], v[28:29], s[98:99] op_sel_hi:[1,0]
	v_pk_mul_f32 v[246:247], v[30:31], s[98:99] op_sel_hi:[1,0]
	v_exp_f32_e32 v244, v244
	v_exp_f32_e32 v245, v245
	v_exp_f32_e32 v246, v246
	v_exp_f32_e32 v247, v247
	v_pk_add_f32 v[244:245], v[244:245], 1.0 op_sel_hi:[1,0]
	v_pk_add_f32 v[246:247], v[246:247], 1.0 op_sel_hi:[1,0]
	v_rcp_f32_e32 v244, v244
	v_rcp_f32_e32 v245, v245
	v_rcp_f32_e32 v246, v246
	v_rcp_f32_e32 v247, v247
	v_pk_mul_f32 v[28:29], v[28:29], v[244:245]
	v_pk_mul_f32 v[30:31], v[30:31], v[246:247]
	v_pk_mul_f32 v[24:25], v[28:29], v[24:25]
	v_pk_mul_f32 v[26:27], v[30:31], v[26:27]
	v_pk_mul_f32 v[244:245], v[20:21], s[98:99] op_sel_hi:[1,0]
	v_pk_mul_f32 v[246:247], v[22:23], s[98:99] op_sel_hi:[1,0]
	v_exp_f32_e32 v244, v244
	v_exp_f32_e32 v245, v245
	v_exp_f32_e32 v246, v246
	v_exp_f32_e32 v247, v247
	v_pk_add_f32 v[244:245], v[244:245], 1.0 op_sel_hi:[1,0]
	v_pk_add_f32 v[246:247], v[246:247], 1.0 op_sel_hi:[1,0]
	v_rcp_f32_e32 v244, v244
	v_rcp_f32_e32 v245, v245
	v_rcp_f32_e32 v246, v246
	v_rcp_f32_e32 v247, v247
	v_pk_mul_f32 v[20:21], v[20:21], v[244:245]
	v_pk_mul_f32 v[22:23], v[22:23], v[246:247]
	v_pk_mul_f32 v[20:21], v[20:21], v[16:17]
	v_pk_mul_f32 v[18:19], v[22:23], v[18:19]
	v_mov_b32_e32 v22, v18
	v_cvt_pk_bf16_f32 v16, v24, v25
	v_cvt_pk_bf16_f32 v17, v26, v27
	v_cvt_pk_bf16_f32 v18, v20, v21
	v_add_u32_e32 v20, 0xa0, v150
	v_mad_i64_i32 v[20:21], s[18:19], v20, s47, v[112:113]
	v_lshl_add_u64 v[20:21], v[20:21], 0, v[114:115]
	v_cvt_pk_bf16_f32 v19, v22, v19
	global_store_dwordx4 v[20:21], v[16:19], off
	s_nop 1
	v_pk_mul_f32 v[244:245], v[12:13], s[98:99] op_sel_hi:[1,0]
	v_pk_mul_f32 v[246:247], v[14:15], s[98:99] op_sel_hi:[1,0]
	v_exp_f32_e32 v244, v244
	v_exp_f32_e32 v245, v245
	v_exp_f32_e32 v246, v246
	v_exp_f32_e32 v247, v247
	v_pk_add_f32 v[244:245], v[244:245], 1.0 op_sel_hi:[1,0]
	v_pk_add_f32 v[246:247], v[246:247], 1.0 op_sel_hi:[1,0]
	v_rcp_f32_e32 v244, v244
	v_rcp_f32_e32 v245, v245
	v_rcp_f32_e32 v246, v246
	v_rcp_f32_e32 v247, v247
	v_pk_mul_f32 v[12:13], v[12:13], v[244:245]
	v_pk_mul_f32 v[14:15], v[14:15], v[246:247]
	v_pk_mul_f32 v[8:9], v[12:13], v[8:9]
	v_pk_mul_f32 v[10:11], v[14:15], v[10:11]
	v_pk_mul_f32 v[244:245], v[4:5], s[98:99] op_sel_hi:[1,0]
	v_pk_mul_f32 v[246:247], v[6:7], s[98:99] op_sel_hi:[1,0]
	v_exp_f32_e32 v244, v244
	v_exp_f32_e32 v245, v245
	v_exp_f32_e32 v246, v246
	v_exp_f32_e32 v247, v247
	v_pk_add_f32 v[244:245], v[244:245], 1.0 op_sel_hi:[1,0]
	v_pk_add_f32 v[246:247], v[246:247], 1.0 op_sel_hi:[1,0]
	v_rcp_f32_e32 v244, v244
	v_rcp_f32_e32 v245, v245
	v_rcp_f32_e32 v246, v246
	v_rcp_f32_e32 v247, v247
	v_pk_mul_f32 v[4:5], v[4:5], v[244:245]
	v_pk_mul_f32 v[6:7], v[6:7], v[246:247]
	v_pk_mul_f32 v[4:5], v[4:5], v[0:1]
	v_pk_mul_f32 v[2:3], v[6:7], v[2:3]
	v_mov_b32_e32 v6, v2
	v_cvt_pk_bf16_f32 v0, v8, v9
	v_cvt_pk_bf16_f32 v1, v10, v11
	v_cvt_pk_bf16_f32 v2, v4, v5
	v_add_u32_e32 v4, 0xb0, v150
	v_mad_i64_i32 v[4:5], s[18:19], v4, s47, v[112:113]
	v_lshl_add_u64 v[4:5], v[4:5], 0, v[114:115]
	s_mov_b64 s[18:19], -1
	v_cvt_pk_bf16_f32 v3, v6, v3
	global_store_dwordx4 v[4:5], v[0:3], off
	s_cbranch_vccnz .LBB0_831
	s_and_b64 vcc, exec, s[62:63]
	s_cbranch_vccnz .LBB0_830
	s_barrier
	s_branch .LBB0_830
